# cache-policy hints: nt on single-use Q loads, gate loads and Y stores of mc_item<2> to keep the shared carried-state block in L2
# speedup vs baseline: 1.0066x; 1.0017x over previous
; #define BSYNC() do { asm volatile("s_waitcnt vmcnt(0) lgkmcnt(0)" ::: "memory"); __syncthreads(); } while (0)
; template <int TY> __device__ __forceinline__ void mc_item(const Params& p, ldsp lds, int item) {
;     ...
;     float rstd[4];
; #pragma unroll
;     for (int tk = 0; tk < 4; ++tk) { float s = 0.f;
; #pragma unroll
;         for (int ei = 0; ei < ET; ++ei) { const f32x4 v = acc[ei][tk]; s += (v[0] * v[0] + v[1] * v[1]) + (v[2] * v[2] + v[3] * v[3]); }
;         s += __shfl_xor(s, 16); s += __shfl_xor(s, 32);
;         if (q4 == 0) RED[wave * 64 + 16 * tk + l15] = s; }
;     BSYNC();
; #pragma unroll
;     for (int tk = 0; tk < 4; ++tk) { float s = 0.f;
; #pragma unroll
;         for (int w = 0; w < 8; ++w) s += RED[w * 64 + 16 * tk + l15];
;         rstd[tk] = rsqrtf(s * (1.0f / DV) + EPS); }
;     const float* nwp = TY == 0 ? p.in[12] : (TY == 1 ? p.in[14] : p.in[17]);
;     const int goff = TY == 0 ? E_RA + h * 128 : (TY == 1 ? E_GB + h * 128 : O_G + h * 512);
;     constexpr int LDY = TY == 2 ? 2048 : 1024; const int ycol = TY == 0 ? h * 128 : (TY == 1 ? 512 + h * 128 : h * 512);
;     bf16_t* Y = (bf16_t*)(p.ws + WS_Y);
; #pragma unroll
;     for (int ei = 0; ei < ET; ++ei) { const int e0 = 16 * (wave * ET + ei) + 4 * q4; const f32x4 w4 = *(const f32x4*)(nwp + e0);
; #pragma unroll
;         for (int tk = 0; tk < 4; ++tk) { const size_t row = (size_t)row0 + 16 * tk + l15;
;             const u32x2 gw = *(const u32x2*)(Pb + row * PP + goff + e0);
.LBB0_877:
	s_or_b64 exec, exec, s[0:1]
	v_or_b32_e32 v72, s9, v151
	s_lshl_b32 s9, s59, 1
	s_add_u32 s0, s26, s9
	s_addc_u32 s1, s27, 0
	v_or_b32_e32 v84, s58, v150
	v_mov_b64_e32 v[90:91], s[0:1]
	s_waitcnt lgkmcnt(0)
	v_mad_i64_i32 v[62:63], s[0:1], v84, s56, v[90:91]
	v_ashrrev_i32_e32 v73, 31, v72
	v_lshl_add_u64 v[74:75], v[62:63], 0, s[48:49]
	v_lshlrev_b64 v[82:83], 1, v[72:73]
	v_lshl_add_u64 v[76:77], v[74:75], 0, v[82:83]
	s_waitcnt vmcnt(0) lgkmcnt(0)
	s_barrier
	global_load_dwordx2 v[186:187], v[76:77], off nt
	v_lshl_add_u64 v[188:189], v[72:73], 2, s[62:63]
	global_load_dwordx4 v[190:193], v[188:189], off
	v_or_b32_e32 v194, s58, v146
	v_mad_i64_i32 v[196:197], s[0:1], v194, s56, v[90:91]
	v_lshl_add_u64 v[198:199], v[196:197], 0, s[48:49]
	v_lshl_add_u64 v[200:201], v[198:199], 0, v[82:83]
	global_load_dwordx2 v[202:203], v[200:201], off nt
	v_or_b32_e32 v204, 32, v84
	v_mad_i64_i32 v[206:207], s[0:1], v204, s56, v[90:91]
	v_lshl_add_u64 v[208:209], v[206:207], 0, s[48:49]
	v_lshl_add_u64 v[210:211], v[208:209], 0, v[82:83]
	v_or_b32_e32 v212, 48, v84
	global_load_dwordx2 v[214:215], v[210:211], off nt
	v_mad_i64_i32 v[216:217], s[0:1], v212, s56, v[90:91]
	v_lshl_add_u64 v[218:219], v[216:217], 0, s[48:49]
	v_lshl_add_u64 v[220:221], v[218:219], 0, v[82:83]
	global_load_dwordx2 v[222:223], v[220:221], off nt
	v_or_b32_e32 v224, 16, v72
	v_ashrrev_i32_e32 v225, 31, v224
	v_lshlrev_b64 v[226:227], 1, v[224:225]
	v_lshl_add_u64 v[228:229], v[74:75], 0, v[226:227]
	global_load_dwordx2 v[230:231], v[228:229], off nt
	global_load_dwordx4 v[232:235], v[188:189], off offset:64
	v_lshl_add_u64 v[236:237], v[198:199], 0, v[226:227]
	global_load_dwordx2 v[238:239], v[236:237], off nt
	v_lshl_add_u64 v[240:241], v[208:209], 0, v[226:227]
	global_load_dwordx2 v[242:243], v[240:241], off nt
	v_lshl_add_u64 v[244:245], v[218:219], 0, v[226:227]
	global_load_dwordx2 v[246:247], v[244:245], off nt
	v_or_b32_e32 v248, 32, v72
	v_ashrrev_i32_e32 v249, 31, v248
	v_lshlrev_b64 v[120:121], 1, v[248:249]
	v_lshl_add_u64 v[122:123], v[74:75], 0, v[120:121]
	global_load_dwordx2 v[124:125], v[122:123], off nt
	v_lshl_add_u64 v[126:127], v[198:199], 0, v[120:121]
	global_load_dwordx4 v[128:131], v[188:189], off offset:128
	global_load_dwordx2 v[132:133], v[126:127], off nt
	v_lshl_add_u64 v[134:135], v[208:209], 0, v[120:121]
	global_load_dwordx2 v[136:137], v[134:135], off nt
	v_lshl_add_u64 v[140:141], v[218:219], 0, v[120:121]
	global_load_dwordx2 v[142:143], v[140:141], off nt
	v_or_b32_e32 v144, 48, v72
	v_ashrrev_i32_e32 v145, 31, v144
	v_lshlrev_b64 v[148:149], 1, v[144:145]
	v_lshl_add_u64 v[152:153], v[74:75], 0, v[148:149]
	global_load_dwordx2 v[154:155], v[152:153], off nt
	v_lshl_add_u64 v[156:157], v[198:199], 0, v[148:149]
	global_load_dwordx4 v[172:175], v[188:189], off offset:192
	global_load_dwordx2 v[158:159], v[156:157], off nt
	v_lshl_add_u64 v[162:163], v[208:209], 0, v[148:149]
	global_load_dwordx2 v[166:167], v[162:163], off nt
	v_lshl_add_u64 v[176:177], v[218:219], 0, v[148:149]
	global_load_dwordx2 v[178:179], v[176:177], off nt
	v_lshl_add_u64 v[70:71], v[72:73], 2, s[62:63]
	v_lshl_add_u32 v16, v150, 2, 0
	v_add_u32_e32 v16, 0x24c00, v16
	ds_read2_b32 v[76:77], v16 offset1:16
	ds_read2_b32 v[80:81], v16 offset0:64 offset1:80
	ds_read2_b32 v[86:87], v16 offset0:128 offset1:144
	ds_read2_b32 v[108:109], v16 offset0:192 offset1:208
	v_add_u32_e32 v73, 0x400, v16
	s_waitcnt lgkmcnt(3)
	v_mov_b32_e32 v118, v77
	v_mov_b32_e32 v119, v76
	s_waitcnt lgkmcnt(2)
	v_mov_b32_e32 v76, v81
	v_mov_b32_e32 v77, v80
	s_waitcnt lgkmcnt(1)
	v_mov_b32_e32 v80, v87
	v_mov_b32_e32 v81, v86
	s_waitcnt lgkmcnt(0)
	v_mov_b32_e32 v86, v109
	v_mov_b32_e32 v87, v108
	v_pk_add_f32 v[108:109], v[118:119], 0 op_sel_hi:[1,0]
	ds_read2_b32 v[106:107], v16 offset0:32 offset1:48
	ds_read2_b32 v[102:103], v16 offset0:96 offset1:112
	ds_read2_b32 v[98:99], v16 offset0:160 offset1:176
	ds_read2_b32 v[94:95], v16 offset0:224 offset1:240
	ds_read2_b32 v[110:111], v73 offset1:16
	ds_read2_b32 v[112:113], v73 offset0:64 offset1:80
	ds_read2_b32 v[114:115], v73 offset0:128 offset1:144
	ds_read2_b32 v[116:117], v73 offset0:192 offset1:208
	ds_read2_b32 v[104:105], v73 offset0:32 offset1:48
	ds_read2_b32 v[100:101], v73 offset0:96 offset1:112
	ds_read2_b32 v[96:97], v73 offset0:160 offset1:176
	ds_read2_b32 v[92:93], v73 offset0:224 offset1:240
	v_pk_add_f32 v[76:77], v[108:109], v[76:77]
	s_waitcnt lgkmcnt(7)
	v_mov_b32_e32 v118, v111
	v_pk_add_f32 v[76:77], v[76:77], v[80:81]
	v_mov_b32_e32 v119, v110
	v_pk_add_f32 v[76:77], v[76:77], v[86:87]
	s_waitcnt lgkmcnt(6)
	v_mov_b32_e32 v110, v113
	v_mov_b32_e32 v111, v112
	v_pk_add_f32 v[76:77], v[76:77], v[118:119]
	s_waitcnt lgkmcnt(5)
	v_mov_b32_e32 v112, v115
	v_mov_b32_e32 v113, v114
	v_pk_add_f32 v[76:77], v[76:77], v[110:111]
	s_mov_b32 s0, 0x358637bd
	s_waitcnt lgkmcnt(4)
	v_mov_b32_e32 v114, v117
	v_mov_b32_e32 v115, v116
	v_pk_add_f32 v[76:77], v[76:77], v[112:113]
	v_mov_b64_e32 v[88:89], s[0:1]
	v_mov_b32_e32 v85, s8
	v_pk_add_f32 v[76:77], v[76:77], v[114:115]
	s_mov_b32 s8, 0x3b000000
	v_pk_fma_f32 v[76:77], v[76:77], s[8:9], v[88:89] op_sel_hi:[1,0,0]
	s_add_u32 s0, s61, s9
	v_mul_f32_e32 v16, 0x4b800000, v77
	v_cmp_gt_f32_e32 vcc, s33, v77
	v_readlane_b32 s1, v253, 31
	s_addc_u32 s1, s1, 0
	v_cndmask_b32_e32 v16, v77, v16, vcc
	v_rsq_f32_e32 v16, v16
	v_lshl_add_u64 v[86:87], s[0:1], 0, v[82:83]
	s_add_i32 s37, s37, s70
	s_add_i32 s36, s36, s70
	v_mul_f32_e32 v73, 0x45800000, v16
	v_cndmask_b32_e32 v16, v16, v73, vcc
	v_pk_mul_f32 v[66:67], v[66:67], v[16:17] op_sel_hi:[1,0]
	v_pk_mul_f32 v[68:69], v[68:69], v[16:17] op_sel_hi:[1,0]
	v_cmp_gt_f32_e32 vcc, s33, v76
	v_pk_mul_f32 v[46:47], v[46:47], v[16:17] op_sel_hi:[1,0]
	v_pk_mul_f32 v[48:49], v[48:49], v[16:17] op_sel_hi:[1,0]
	v_pk_mul_f32 v[30:31], v[30:31], v[16:17] op_sel_hi:[1,0]
	v_pk_mul_f32 v[32:33], v[32:33], v[16:17] op_sel_hi:[1,0]
	v_pk_mul_f32 v[12:13], v[12:13], v[16:17] op_sel_hi:[1,0]
	v_pk_mul_f32 v[14:15], v[14:15], v[16:17] op_sel_hi:[1,0]
	s_cmpk_lt_i32 s37, 0x400
	s_waitcnt vmcnt(0)
; __device__ __forceinline__ unsigned pk2(float lo, float hi) { return pg8::cvt_pk_bf16(lo, hi); }
; __device__ __forceinline__ float siluf(float x) { return x * __builtin_amdgcn_rcpf(1.0f + __expf(-x)); }
; template <int TY> __device__ __forceinline__ void mc_item(const Params& p, ldsp lds, int item) {
;     ...
;     for (int ei = 0; ei < ET; ++ei) { const int e0 = 16 * (wave * ET + ei) + 4 * q4; const f32x4 w4 = *(const f32x4*)(nwp + e0);
; #pragma unroll
;         for (int tk = 0; tk < 4; ++tk) { const size_t row = (size_t)row0 + 16 * tk + l15;
;             const u32x2 gw = *(const u32x2*)(Pb + row * PP + goff + e0);
;             const float g0 = bf2f(gw.x & 0xffffu), g1 = bf2f(gw.x >> 16), g2 = bf2f(gw.y & 0xffffu), g3 = bf2f(gw.y >> 16);
;             const f32x4 v = acc[ei][tk] * rstd[tk] * w4;
;             float y0 = v[0] * siluf(g0), y1 = v[1] * siluf(g1), y2 = v[2] * siluf(g2), y3 = v[3] * siluf(g3);
;     ...
;             if (!(fabsf(y0) < 1e30f)) y0 = 0.f; if (!(fabsf(y1) < 1e30f)) y1 = 0.f; if (!(fabsf(y2) < 1e30f)) y2 = 0.f; if (!(fabsf(y3) < 1e30f)) y3 = 0.f;
;     ...
;             u32x2 o; o.x = pk2(y0, y1); o.y = pk2(y2, y3);
;             *(u32x2*)(Y + row * LDY + ycol + e0) = o; } }
	v_lshlrev_b32_e32 v73, 16, v186
	v_mul_f32_e32 v80, 0xbfb8aa3b, v73
	v_exp_f32_e32 v80, v80
	v_and_b32_e32 v77, 0xffff0000, v186
	v_lshlrev_b32_e32 v78, 16, v187
	v_and_b32_e32 v79, 0xffff0000, v187
	v_mul_f32_e32 v81, 0xbfb8aa3b, v77
	v_mul_f32_e32 v108, 0xbfb8aa3b, v78
	v_mul_f32_e32 v109, 0xbfb8aa3b, v79
	v_exp_f32_e32 v81, v81
	v_add_f32_e32 v80, 1.0, v80
	v_exp_f32_e32 v108, v108
	v_exp_f32_e32 v109, v109
	v_rcp_f32_e32 v80, v80
	v_add_f32_e32 v81, 1.0, v81
	v_pk_mul_f32 v[66:67], v[66:67], v[190:191]
	v_add_f32_e32 v108, 1.0, v108
	v_rcp_f32_e32 v81, v81
	v_add_f32_e32 v109, 1.0, v109
	v_mul_f32_e32 v73, v80, v73
	v_rcp_f32_e32 v108, v108
	v_mul_f32_e32 v66, v66, v73
	v_rcp_f32_e32 v73, v109
	v_mul_f32_e32 v77, v81, v77
	v_pk_mul_f32 v[68:69], v[68:69], v[192:193]
	v_mul_f32_e32 v67, v67, v77
	v_mul_f32_e32 v77, v108, v78
	v_mul_f32_e32 v73, v73, v79
	v_mul_f32_e32 v68, v68, v77
	v_mul_f32_e32 v69, v69, v73
	v_cvt_pk_bf16_f32 v66, v66, v67
	v_cvt_pk_bf16_f32 v67, v68, v69
	v_lshlrev_b64 v[68:69], 12, v[84:85]
	v_lshl_add_u64 v[78:79], v[86:87], 0, v[68:69]
	global_store_dwordx2 v[78:79], v[66:67], off nt
	v_or_b32_e32 v66, s58, v146
	v_mad_i64_i32 v[68:69], s[0:1], v66, s56, v[90:91]
	v_lshl_add_u64 v[80:81], v[68:69], 0, s[48:49]
	v_lshl_add_u64 v[68:69], v[80:81], 0, v[82:83]
	v_mul_f32_e32 v73, 0x4b800000, v76
	v_cndmask_b32_e32 v73, v76, v73, vcc
	v_rsq_f32_e32 v73, v73
	v_mov_b32_e32 v67, v85
	v_or_b32_e32 v108, 32, v84
	v_lshlrev_b64 v[66:67], 12, v[66:67]
	v_mul_f32_e32 v76, 0x45800000, v73
	v_cndmask_b32_e32 v76, v73, v76, vcc
	v_pk_mul_f32 v[58:59], v[58:59], v[76:77] op_sel_hi:[1,0]
	v_pk_mul_f32 v[60:61], v[60:61], v[76:77] op_sel_hi:[1,0]
	v_mad_i64_i32 v[68:69], s[0:1], v108, s56, v[90:91]
	v_pk_mul_f32 v[58:59], v[58:59], v[190:191]
	v_lshl_add_u64 v[68:69], v[68:69], 0, s[48:49]
	v_lshl_add_u64 v[66:67], v[86:87], 0, v[66:67]
	v_pk_mul_f32 v[60:61], v[60:61], v[192:193]
	v_lshl_add_u64 v[112:113], v[68:69], 0, v[82:83]
	v_or_b32_e32 v84, 48, v84
	v_lshlrev_b32_e32 v73, 16, v202
	v_and_b32_e32 v77, 0xffff0000, v202
	v_lshlrev_b32_e32 v109, 16, v203
	v_and_b32_e32 v110, 0xffff0000, v203
	v_mul_f32_e32 v111, 0xbfb8aa3b, v73
	v_mul_f32_e32 v114, 0xbfb8aa3b, v77
	v_mul_f32_e32 v115, 0xbfb8aa3b, v109
	v_mul_f32_e32 v116, 0xbfb8aa3b, v110
	v_exp_f32_e32 v111, v111
	v_exp_f32_e32 v114, v114
	v_exp_f32_e32 v115, v115
	v_exp_f32_e32 v116, v116
	v_add_f32_e32 v111, 1.0, v111
	v_add_f32_e32 v114, 1.0, v114
	v_add_f32_e32 v115, 1.0, v115
	v_add_f32_e32 v116, 1.0, v116
	v_rcp_f32_e32 v111, v111
	v_rcp_f32_e32 v114, v114
	v_rcp_f32_e32 v115, v115
	v_rcp_f32_e32 v116, v116
	v_mul_f32_e32 v73, v111, v73
	v_mul_f32_e32 v77, v114, v77
	v_mul_f32_e32 v109, v115, v109
	v_mul_f32_e32 v110, v116, v110
	v_mul_f32_e32 v58, v58, v73
	v_mul_f32_e32 v59, v59, v77
	v_mul_f32_e32 v60, v60, v109
	v_mul_f32_e32 v61, v61, v110
	v_cvt_pk_bf16_f32 v58, v58, v59
	v_cvt_pk_bf16_f32 v59, v60, v61
	global_store_dwordx2 v[66:67], v[58:59], off nt
	v_mad_i64_i32 v[60:61], s[0:1], v84, s56, v[90:91]
	v_mov_b32_e32 v90, v107
	v_mov_b32_e32 v91, v106
	v_mov_b32_e32 v106, v103
	v_mov_b32_e32 v107, v102
	v_pk_add_f32 v[90:91], v[90:91], 0 op_sel_hi:[1,0]
	v_mov_b32_e32 v102, v99
	v_mov_b32_e32 v103, v98
	v_pk_add_f32 v[90:91], v[90:91], v[106:107]
	v_mov_b32_e32 v98, v95
	v_mov_b32_e32 v99, v94
	v_pk_add_f32 v[90:91], v[90:91], v[102:103]
	s_waitcnt lgkmcnt(3)
	v_mov_b32_e32 v94, v105
	v_mov_b32_e32 v95, v104
	v_pk_add_f32 v[90:91], v[90:91], v[98:99]
	s_waitcnt lgkmcnt(2)
	v_mov_b32_e32 v104, v101
	v_mov_b32_e32 v105, v100
	v_pk_add_f32 v[90:91], v[90:91], v[94:95]
	s_waitcnt lgkmcnt(1)
	v_mov_b32_e32 v100, v97
	v_mov_b32_e32 v101, v96
	v_pk_add_f32 v[90:91], v[90:91], v[104:105]
	s_waitcnt lgkmcnt(0)
	v_mov_b32_e32 v96, v93
	v_mov_b32_e32 v97, v92
	v_pk_add_f32 v[90:91], v[90:91], v[100:101]
	v_lshl_add_u64 v[60:61], v[60:61], 0, s[48:49]
	v_pk_add_f32 v[90:91], v[90:91], v[96:97]
	v_mov_b32_e32 v109, v85
	v_pk_fma_f32 v[88:89], v[90:91], s[8:9], v[88:89] op_sel_hi:[1,0,0]
	v_lshl_add_u64 v[90:91], v[60:61], 0, v[82:83]
	v_mul_f32_e32 v73, 0x4b800000, v89
	v_cmp_gt_f32_e32 vcc, s33, v89
	v_lshlrev_b64 v[58:59], 12, v[108:109]
	v_lshl_add_u64 v[58:59], v[86:87], 0, v[58:59]
	v_cndmask_b32_e32 v73, v89, v73, vcc
	v_rsq_f32_e32 v73, v73
	v_and_b32_e32 v89, 0xffff0000, v215
	v_mul_f32_e32 v77, 0x45800000, v73
	v_cndmask_b32_e32 v82, v73, v77, vcc
	v_lshlrev_b32_e32 v73, 16, v214
	v_and_b32_e32 v77, 0xffff0000, v214
	v_pk_mul_f32 v[54:55], v[54:55], v[82:83] op_sel_hi:[1,0]
	v_pk_mul_f32 v[56:57], v[56:57], v[82:83] op_sel_hi:[1,0]
	v_lshlrev_b32_e32 v83, 16, v215
	v_mul_f32_e32 v92, 0xbfb8aa3b, v73
	v_mul_f32_e32 v93, 0xbfb8aa3b, v77
	v_mul_f32_e32 v94, 0xbfb8aa3b, v83
	v_mul_f32_e32 v95, 0xbfb8aa3b, v89
	v_exp_f32_e32 v92, v92
	v_exp_f32_e32 v93, v93
	v_exp_f32_e32 v94, v94
	v_exp_f32_e32 v95, v95
	v_add_f32_e32 v92, 1.0, v92
	v_add_f32_e32 v93, 1.0, v93
	v_add_f32_e32 v94, 1.0, v94
	v_add_f32_e32 v95, 1.0, v95
	v_rcp_f32_e32 v92, v92
	v_rcp_f32_e32 v93, v93
	v_rcp_f32_e32 v94, v94
	v_rcp_f32_e32 v95, v95
	v_pk_mul_f32 v[54:55], v[190:191], v[54:55]
	v_mul_f32_e32 v73, v92, v73
	v_mul_f32_e32 v77, v93, v77
	v_pk_mul_f32 v[56:57], v[192:193], v[56:57]
	v_mul_f32_e32 v83, v94, v83
	v_mul_f32_e32 v89, v95, v89
	v_mul_f32_e32 v54, v54, v73
	v_mul_f32_e32 v55, v55, v77
	v_mul_f32_e32 v56, v56, v83
	v_mul_f32_e32 v57, v57, v89
	v_cvt_pk_bf16_f32 v54, v54, v55
	v_cvt_pk_bf16_f32 v55, v56, v57
	global_store_dwordx2 v[58:59], v[54:55], off nt
	v_mul_f32_e32 v57, 0x4b800000, v88
	v_cmp_gt_f32_e32 vcc, s33, v88
	v_or_b32_e32 v56, 16, v72
	s_nop 0
	v_cndmask_b32_e32 v57, v88, v57, vcc
; __device__ __forceinline__ unsigned pk2(float lo, float hi) { return pg8::cvt_pk_bf16(lo, hi); }
; __device__ __forceinline__ float siluf(float x) { return x * __builtin_amdgcn_rcpf(1.0f + __expf(-x)); }
; template <int TY> __device__ __forceinline__ void mc_item(const Params& p, ldsp lds, int item) {
;     ...
;     for (int ei = 0; ei < ET; ++ei) { const int e0 = 16 * (wave * ET + ei) + 4 * q4; const f32x4 w4 = *(const f32x4*)(nwp + e0);
; #pragma unroll
;         for (int tk = 0; tk < 4; ++tk) { const size_t row = (size_t)row0 + 16 * tk + l15;
;             const u32x2 gw = *(const u32x2*)(Pb + row * PP + goff + e0);
;             const float g0 = bf2f(gw.x & 0xffffu), g1 = bf2f(gw.x >> 16), g2 = bf2f(gw.y & 0xffffu), g3 = bf2f(gw.y >> 16);
;             const f32x4 v = acc[ei][tk] * rstd[tk] * w4;
;             float y0 = v[0] * siluf(g0), y1 = v[1] * siluf(g1), y2 = v[2] * siluf(g2), y3 = v[3] * siluf(g3);
;     ...
;             if (!(fabsf(y0) < 1e30f)) y0 = 0.f; if (!(fabsf(y1) < 1e30f)) y1 = 0.f; if (!(fabsf(y2) < 1e30f)) y2 = 0.f; if (!(fabsf(y3) < 1e30f)) y3 = 0.f;
;     ...
;             u32x2 o; o.x = pk2(y0, y1); o.y = pk2(y2, y3);
;             *(u32x2*)(Y + row * LDY + ycol + e0) = o; } }
	v_rsq_f32_e32 v73, v57
	v_ashrrev_i32_e32 v57, 31, v56
	v_lshlrev_b64 v[88:89], 1, v[56:57]
	v_lshl_add_u64 v[90:91], v[74:75], 0, v[88:89]
	v_mul_f32_e32 v56, 0x45800000, v73
	v_cndmask_b32_e32 v56, v73, v56, vcc
	v_pk_mul_f32 v[50:51], v[50:51], v[56:57] op_sel_hi:[1,0]
	v_pk_mul_f32 v[52:53], v[52:53], v[56:57] op_sel_hi:[1,0]
	v_pk_mul_f32 v[50:51], v[190:191], v[50:51]
	v_pk_mul_f32 v[52:53], v[192:193], v[52:53]
	v_lshlrev_b32_e32 v57, 16, v222
	v_and_b32_e32 v54, 0xffff0000, v222
	v_lshlrev_b32_e32 v62, 16, v223
	v_and_b32_e32 v55, 0xffff0000, v223
	v_mul_f32_e32 v63, 0xbfb8aa3b, v57
	v_mul_f32_e32 v64, 0xbfb8aa3b, v54
	v_mul_f32_e32 v65, 0xbfb8aa3b, v62
	v_mul_f32_e32 v73, 0xbfb8aa3b, v55
	v_exp_f32_e32 v63, v63
	v_exp_f32_e32 v64, v64
	v_exp_f32_e32 v65, v65
	v_exp_f32_e32 v73, v73
	v_add_f32_e32 v63, 1.0, v63
	v_add_f32_e32 v64, 1.0, v64
	v_add_f32_e32 v65, 1.0, v65
	v_add_f32_e32 v73, 1.0, v73
	v_rcp_f32_e32 v63, v63
	v_rcp_f32_e32 v64, v64
	v_rcp_f32_e32 v65, v65
	v_rcp_f32_e32 v73, v73
	v_mul_f32_e32 v57, v63, v57
	v_mul_f32_e32 v54, v64, v54
	v_mul_f32_e32 v62, v65, v62
	v_mul_f32_e32 v55, v73, v55
	v_mul_f32_e32 v50, v50, v57
	v_mul_f32_e32 v51, v51, v54
	v_mul_f32_e32 v52, v52, v62
	v_mul_f32_e32 v53, v53, v55
	v_cvt_pk_bf16_f32 v50, v50, v51
	v_cvt_pk_bf16_f32 v51, v52, v53
	v_lshlrev_b64 v[52:53], 12, v[84:85]
	v_lshl_add_u64 v[54:55], v[86:87], 0, v[52:53]
	global_store_dwordx2 v[54:55], v[50:51], off nt
	v_lshl_add_u64 v[64:65], v[80:81], 0, v[88:89]
	v_lshlrev_b32_e32 v57, 16, v230
	v_and_b32_e32 v62, 0xffff0000, v230
	v_lshlrev_b32_e32 v73, 16, v231
	v_and_b32_e32 v63, 0xffff0000, v231
	v_mul_f32_e32 v77, 0xbfb8aa3b, v57
	v_mul_f32_e32 v83, 0xbfb8aa3b, v62
	v_mul_f32_e32 v84, 0xbfb8aa3b, v73
	v_mul_f32_e32 v85, 0xbfb8aa3b, v63
	v_exp_f32_e32 v77, v77
	v_exp_f32_e32 v83, v83
	v_exp_f32_e32 v84, v84
	v_exp_f32_e32 v85, v85
	v_add_f32_e32 v77, 1.0, v77
	v_add_f32_e32 v83, 1.0, v83
	v_add_f32_e32 v84, 1.0, v84
	v_add_f32_e32 v85, 1.0, v85
	v_rcp_f32_e32 v77, v77
	v_rcp_f32_e32 v83, v83
	v_rcp_f32_e32 v84, v84
	v_rcp_f32_e32 v85, v85
	v_pk_mul_f32 v[46:47], v[46:47], v[232:233]
	v_mul_f32_e32 v57, v77, v57
	v_mul_f32_e32 v62, v83, v62
	v_pk_mul_f32 v[48:49], v[48:49], v[234:235]
	v_mul_f32_e32 v73, v84, v73
	v_mul_f32_e32 v63, v85, v63
	v_mul_f32_e32 v46, v46, v57
	v_mul_f32_e32 v47, v47, v62
	v_mul_f32_e32 v48, v48, v73
	v_mul_f32_e32 v49, v49, v63
	v_cvt_pk_bf16_f32 v46, v46, v47
	v_cvt_pk_bf16_f32 v47, v48, v49
	global_store_dwordx2 v[78:79], v[46:47], off offset:32 nt
	v_pk_mul_f32 v[42:43], v[42:43], v[76:77] op_sel_hi:[1,0]
	v_pk_mul_f32 v[44:45], v[44:45], v[76:77] op_sel_hi:[1,0]
	v_pk_mul_f32 v[42:43], v[42:43], v[232:233]
	v_pk_mul_f32 v[44:45], v[44:45], v[234:235]
	v_lshl_add_u64 v[48:49], v[68:69], 0, v[88:89]
	v_pk_mul_f32 v[38:39], v[38:39], v[82:83] op_sel_hi:[1,0]
	v_pk_mul_f32 v[40:41], v[40:41], v[82:83] op_sel_hi:[1,0]
	v_pk_mul_f32 v[38:39], v[38:39], v[232:233]
	v_pk_mul_f32 v[40:41], v[40:41], v[234:235]
	v_pk_mul_f32 v[26:27], v[26:27], v[76:77] op_sel_hi:[1,0]
	v_pk_mul_f32 v[28:29], v[28:29], v[76:77] op_sel_hi:[1,0]
	v_pk_mul_f32 v[22:23], v[22:23], v[82:83] op_sel_hi:[1,0]
	v_pk_mul_f32 v[24:25], v[24:25], v[82:83] op_sel_hi:[1,0]
	v_pk_mul_f32 v[8:9], v[8:9], v[76:77] op_sel_hi:[1,0]
	v_pk_mul_f32 v[10:11], v[10:11], v[76:77] op_sel_hi:[1,0]
	v_pk_mul_f32 v[4:5], v[4:5], v[82:83] op_sel_hi:[1,0]
	v_pk_mul_f32 v[6:7], v[6:7], v[82:83] op_sel_hi:[1,0]
	v_lshlrev_b32_e32 v57, 16, v238
	v_and_b32_e32 v46, 0xffff0000, v238
	v_lshlrev_b32_e32 v62, 16, v239
	v_and_b32_e32 v47, 0xffff0000, v239
	v_mul_f32_e32 v63, 0xbfb8aa3b, v57
	v_mul_f32_e32 v64, 0xbfb8aa3b, v46
	v_mul_f32_e32 v65, 0xbfb8aa3b, v62
	v_mul_f32_e32 v73, 0xbfb8aa3b, v47
	v_exp_f32_e32 v63, v63
	v_exp_f32_e32 v64, v64
	v_exp_f32_e32 v65, v65
	v_exp_f32_e32 v73, v73
	v_add_f32_e32 v63, 1.0, v63
	v_add_f32_e32 v64, 1.0, v64
	v_add_f32_e32 v65, 1.0, v65
	v_add_f32_e32 v73, 1.0, v73
	v_rcp_f32_e32 v63, v63
	v_rcp_f32_e32 v64, v64
	v_rcp_f32_e32 v65, v65
	v_rcp_f32_e32 v73, v73
	v_mul_f32_e32 v57, v63, v57
	v_mul_f32_e32 v46, v64, v46
	v_mul_f32_e32 v62, v65, v62
	v_mul_f32_e32 v47, v73, v47
	v_mul_f32_e32 v42, v42, v57
	v_mul_f32_e32 v43, v43, v46
	v_mul_f32_e32 v44, v44, v62
	v_mul_f32_e32 v45, v45, v47
	v_cvt_pk_bf16_f32 v42, v42, v43
	v_cvt_pk_bf16_f32 v43, v44, v45
	global_store_dwordx2 v[66:67], v[42:43], off offset:32 nt
	v_lshl_add_u64 v[44:45], v[60:61], 0, v[88:89]
	v_lshlrev_b32_e32 v46, 16, v242
	v_and_b32_e32 v42, 0xffff0000, v242
	v_lshlrev_b32_e32 v47, 16, v243
	v_and_b32_e32 v43, 0xffff0000, v243
	v_mul_f32_e32 v48, 0xbfb8aa3b, v46
	v_mul_f32_e32 v49, 0xbfb8aa3b, v42
	v_mul_f32_e32 v57, 0xbfb8aa3b, v47
	v_mul_f32_e32 v62, 0xbfb8aa3b, v43
	v_exp_f32_e32 v48, v48
	v_exp_f32_e32 v49, v49
	v_exp_f32_e32 v57, v57
	v_exp_f32_e32 v62, v62
	v_add_f32_e32 v48, 1.0, v48
	v_add_f32_e32 v49, 1.0, v49
	v_add_f32_e32 v57, 1.0, v57
	v_add_f32_e32 v62, 1.0, v62
	v_rcp_f32_e32 v48, v48
	v_rcp_f32_e32 v49, v49
	v_rcp_f32_e32 v57, v57
	v_rcp_f32_e32 v62, v62
	v_mul_f32_e32 v46, v48, v46
	v_mul_f32_e32 v42, v49, v42
	v_mul_f32_e32 v47, v57, v47
	v_mul_f32_e32 v43, v62, v43
	v_mul_f32_e32 v38, v38, v46
	v_mul_f32_e32 v39, v39, v42
	v_mul_f32_e32 v40, v40, v47
	v_mul_f32_e32 v41, v41, v43
	v_cvt_pk_bf16_f32 v38, v38, v39
	v_cvt_pk_bf16_f32 v39, v40, v41
	global_store_dwordx2 v[58:59], v[38:39], off offset:32 nt
	v_or_b32_e32 v38, 32, v72
	v_ashrrev_i32_e32 v39, 31, v38
	v_pk_mul_f32 v[34:35], v[34:35], v[56:57] op_sel_hi:[1,0]
	v_lshlrev_b64 v[38:39], 1, v[38:39]
	v_pk_mul_f32 v[36:37], v[36:37], v[56:57] op_sel_hi:[1,0]
; __device__ __forceinline__ unsigned pk2(float lo, float hi) { return pg8::cvt_pk_bf16(lo, hi); }
; __device__ __forceinline__ float siluf(float x) { return x * __builtin_amdgcn_rcpf(1.0f + __expf(-x)); }
; template <int TY> __device__ __forceinline__ void mc_item(const Params& p, ldsp lds, int item) {
;     ...
;     for (int ei = 0; ei < ET; ++ei) { const int e0 = 16 * (wave * ET + ei) + 4 * q4; const f32x4 w4 = *(const f32x4*)(nwp + e0);
; #pragma unroll
;         for (int tk = 0; tk < 4; ++tk) { const size_t row = (size_t)row0 + 16 * tk + l15;
;             const u32x2 gw = *(const u32x2*)(Pb + row * PP + goff + e0);
;             const float g0 = bf2f(gw.x & 0xffffu), g1 = bf2f(gw.x >> 16), g2 = bf2f(gw.y & 0xffffu), g3 = bf2f(gw.y >> 16);
;             const f32x4 v = acc[ei][tk] * rstd[tk] * w4;
;             float y0 = v[0] * siluf(g0), y1 = v[1] * siluf(g1), y2 = v[2] * siluf(g2), y3 = v[3] * siluf(g3);
;     ...
;             if (!(fabsf(y0) < 1e30f)) y0 = 0.f; if (!(fabsf(y1) < 1e30f)) y1 = 0.f; if (!(fabsf(y2) < 1e30f)) y2 = 0.f; if (!(fabsf(y3) < 1e30f)) y3 = 0.f;
;     ...
;             u32x2 o; o.x = pk2(y0, y1); o.y = pk2(y2, y3);
;             *(u32x2*)(Y + row * LDY + ycol + e0) = o; } }
	v_pk_mul_f32 v[34:35], v[34:35], v[232:233]
	v_lshl_add_u64 v[42:43], v[74:75], 0, v[38:39]
	v_pk_mul_f32 v[36:37], v[36:37], v[234:235]
	v_pk_mul_f32 v[18:19], v[18:19], v[56:57] op_sel_hi:[1,0]
	v_pk_mul_f32 v[20:21], v[20:21], v[56:57] op_sel_hi:[1,0]
	v_pk_mul_f32 v[0:1], v[0:1], v[56:57] op_sel_hi:[1,0]
	v_pk_mul_f32 v[2:3], v[2:3], v[56:57] op_sel_hi:[1,0]
	v_lshlrev_b32_e32 v44, 16, v246
	v_and_b32_e32 v40, 0xffff0000, v246
	v_lshlrev_b32_e32 v45, 16, v247
	v_and_b32_e32 v41, 0xffff0000, v247
	v_mul_f32_e32 v46, 0xbfb8aa3b, v44
	v_mul_f32_e32 v47, 0xbfb8aa3b, v40
	v_mul_f32_e32 v48, 0xbfb8aa3b, v45
	v_mul_f32_e32 v49, 0xbfb8aa3b, v41
	v_exp_f32_e32 v46, v46
	v_exp_f32_e32 v47, v47
	v_exp_f32_e32 v48, v48
	v_exp_f32_e32 v49, v49
	v_add_f32_e32 v46, 1.0, v46
	v_add_f32_e32 v47, 1.0, v47
	v_add_f32_e32 v48, 1.0, v48
	v_add_f32_e32 v49, 1.0, v49
	v_rcp_f32_e32 v46, v46
	v_rcp_f32_e32 v47, v47
	v_rcp_f32_e32 v48, v48
	v_rcp_f32_e32 v49, v49
	v_mul_f32_e32 v44, v46, v44
	v_mul_f32_e32 v40, v47, v40
	v_mul_f32_e32 v45, v48, v45
	v_mul_f32_e32 v41, v49, v41
	v_mul_f32_e32 v34, v34, v44
	v_mul_f32_e32 v35, v35, v40
	v_mul_f32_e32 v36, v36, v45
	v_mul_f32_e32 v37, v37, v41
	v_cvt_pk_bf16_f32 v34, v34, v35
	v_cvt_pk_bf16_f32 v35, v36, v37
	v_lshl_add_u64 v[42:43], v[80:81], 0, v[38:39]
	global_store_dwordx2 v[54:55], v[34:35], off offset:32 nt
	v_lshlrev_b32_e32 v44, 16, v124
	v_and_b32_e32 v40, 0xffff0000, v124
	v_lshlrev_b32_e32 v45, 16, v125
	v_and_b32_e32 v41, 0xffff0000, v125
	v_mul_f32_e32 v46, 0xbfb8aa3b, v44
	v_mul_f32_e32 v47, 0xbfb8aa3b, v40
	v_mul_f32_e32 v48, 0xbfb8aa3b, v45
	v_mul_f32_e32 v49, 0xbfb8aa3b, v41
	v_exp_f32_e32 v46, v46
	v_exp_f32_e32 v47, v47
	v_exp_f32_e32 v48, v48
	v_exp_f32_e32 v49, v49
	v_add_f32_e32 v46, 1.0, v46
	v_add_f32_e32 v47, 1.0, v47
	v_add_f32_e32 v48, 1.0, v48
	v_add_f32_e32 v49, 1.0, v49
	v_rcp_f32_e32 v46, v46
	v_rcp_f32_e32 v47, v47
	v_rcp_f32_e32 v48, v48
	v_rcp_f32_e32 v49, v49
	v_pk_mul_f32 v[30:31], v[30:31], v[128:129]
	v_mul_f32_e32 v44, v46, v44
	v_mul_f32_e32 v40, v47, v40
	v_pk_mul_f32 v[32:33], v[32:33], v[130:131]
	v_mul_f32_e32 v45, v48, v45
	v_mul_f32_e32 v41, v49, v41
	v_mul_f32_e32 v30, v30, v44
	v_mul_f32_e32 v31, v31, v40
	v_mul_f32_e32 v32, v32, v45
	v_mul_f32_e32 v33, v33, v41
	v_cvt_pk_bf16_f32 v30, v30, v31
	v_cvt_pk_bf16_f32 v31, v32, v33
	global_store_dwordx2 v[78:79], v[30:31], off offset:64 nt
	v_pk_mul_f32 v[26:27], v[26:27], v[128:129]
	v_pk_mul_f32 v[28:29], v[28:29], v[130:131]
	v_lshl_add_u64 v[32:33], v[68:69], 0, v[38:39]
	v_pk_mul_f32 v[22:23], v[22:23], v[128:129]
	v_pk_mul_f32 v[24:25], v[24:25], v[130:131]
	v_pk_mul_f32 v[18:19], v[18:19], v[128:129]
	v_pk_mul_f32 v[20:21], v[20:21], v[130:131]
	v_lshlrev_b32_e32 v40, 16, v132
	v_and_b32_e32 v30, 0xffff0000, v132
	v_lshlrev_b32_e32 v41, 16, v133
	v_and_b32_e32 v31, 0xffff0000, v133
	v_mul_f32_e32 v42, 0xbfb8aa3b, v40
	v_mul_f32_e32 v43, 0xbfb8aa3b, v30
	v_mul_f32_e32 v44, 0xbfb8aa3b, v41
	v_mul_f32_e32 v45, 0xbfb8aa3b, v31
	v_exp_f32_e32 v42, v42
	v_exp_f32_e32 v43, v43
	v_exp_f32_e32 v44, v44
	v_exp_f32_e32 v45, v45
	v_add_f32_e32 v42, 1.0, v42
	v_add_f32_e32 v43, 1.0, v43
	v_add_f32_e32 v44, 1.0, v44
	v_add_f32_e32 v45, 1.0, v45
	v_rcp_f32_e32 v42, v42
	v_rcp_f32_e32 v43, v43
	v_rcp_f32_e32 v44, v44
	v_rcp_f32_e32 v45, v45
	v_mul_f32_e32 v40, v42, v40
	v_mul_f32_e32 v30, v43, v30
	v_mul_f32_e32 v41, v44, v41
	v_mul_f32_e32 v31, v45, v31
	v_mul_f32_e32 v26, v26, v40
	v_mul_f32_e32 v27, v27, v30
	v_mul_f32_e32 v28, v28, v41
	v_mul_f32_e32 v29, v29, v31
	v_cvt_pk_bf16_f32 v26, v26, v27
	v_cvt_pk_bf16_f32 v27, v28, v29
	global_store_dwordx2 v[66:67], v[26:27], off offset:64 nt
	v_lshl_add_u64 v[28:29], v[60:61], 0, v[38:39]
	v_lshlrev_b32_e32 v30, 16, v136
	v_and_b32_e32 v26, 0xffff0000, v136
	v_lshlrev_b32_e32 v31, 16, v137
	v_and_b32_e32 v27, 0xffff0000, v137
	v_mul_f32_e32 v32, 0xbfb8aa3b, v30
	v_mul_f32_e32 v33, 0xbfb8aa3b, v26
	v_mul_f32_e32 v38, 0xbfb8aa3b, v31
	v_mul_f32_e32 v39, 0xbfb8aa3b, v27
	v_exp_f32_e32 v32, v32
	v_exp_f32_e32 v33, v33
	v_exp_f32_e32 v38, v38
	v_exp_f32_e32 v39, v39
	v_add_f32_e32 v32, 1.0, v32
	v_add_f32_e32 v33, 1.0, v33
	v_add_f32_e32 v38, 1.0, v38
	v_add_f32_e32 v39, 1.0, v39
	v_rcp_f32_e32 v32, v32
	v_rcp_f32_e32 v33, v33
	v_rcp_f32_e32 v38, v38
	v_rcp_f32_e32 v39, v39
	v_mul_f32_e32 v30, v32, v30
	v_mul_f32_e32 v26, v33, v26
	v_mul_f32_e32 v31, v38, v31
	v_mul_f32_e32 v27, v39, v27
	v_mul_f32_e32 v22, v22, v30
	v_mul_f32_e32 v23, v23, v26
	v_mul_f32_e32 v24, v24, v31
	v_mul_f32_e32 v25, v25, v27
	v_cvt_pk_bf16_f32 v22, v22, v23
	v_cvt_pk_bf16_f32 v23, v24, v25
	global_store_dwordx2 v[58:59], v[22:23], off offset:64 nt
	v_or_b32_e32 v22, 48, v72
	v_ashrrev_i32_e32 v23, 31, v22
	v_lshlrev_b64 v[22:23], 1, v[22:23]
	v_lshl_add_u64 v[26:27], v[74:75], 0, v[22:23]
	v_lshlrev_b32_e32 v28, 16, v142
	v_and_b32_e32 v24, 0xffff0000, v142
	v_lshlrev_b32_e32 v29, 16, v143
	v_and_b32_e32 v25, 0xffff0000, v143
	v_mul_f32_e32 v30, 0xbfb8aa3b, v28
	v_mul_f32_e32 v31, 0xbfb8aa3b, v24
	v_mul_f32_e32 v32, 0xbfb8aa3b, v29
	v_mul_f32_e32 v33, 0xbfb8aa3b, v25
	v_exp_f32_e32 v30, v30
	v_exp_f32_e32 v31, v31
	v_exp_f32_e32 v32, v32
	v_exp_f32_e32 v33, v33
	v_add_f32_e32 v30, 1.0, v30
	v_add_f32_e32 v31, 1.0, v31
	v_add_f32_e32 v32, 1.0, v32
	v_add_f32_e32 v33, 1.0, v33
	v_rcp_f32_e32 v30, v30
	v_rcp_f32_e32 v31, v31
	v_rcp_f32_e32 v32, v32
	v_rcp_f32_e32 v33, v33
	v_mul_f32_e32 v28, v30, v28
	v_mul_f32_e32 v24, v31, v24
	v_mul_f32_e32 v29, v32, v29
	v_mul_f32_e32 v25, v33, v25
	v_mul_f32_e32 v18, v18, v28
	v_mul_f32_e32 v19, v19, v24
	v_mul_f32_e32 v20, v20, v29
	v_mul_f32_e32 v21, v21, v25
; __device__ __forceinline__ unsigned pk2(float lo, float hi) { return pg8::cvt_pk_bf16(lo, hi); }
; __device__ __forceinline__ float siluf(float x) { return x * __builtin_amdgcn_rcpf(1.0f + __expf(-x)); }
; template <int TY> __device__ __forceinline__ void mc_item(const Params& p, ldsp lds, int item) {
;     ...
;     for (int ei = 0; ei < ET; ++ei) { const int e0 = 16 * (wave * ET + ei) + 4 * q4; const f32x4 w4 = *(const f32x4*)(nwp + e0);
; #pragma unroll
;         for (int tk = 0; tk < 4; ++tk) { const size_t row = (size_t)row0 + 16 * tk + l15;
;             const u32x2 gw = *(const u32x2*)(Pb + row * PP + goff + e0);
;             const float g0 = bf2f(gw.x & 0xffffu), g1 = bf2f(gw.x >> 16), g2 = bf2f(gw.y & 0xffffu), g3 = bf2f(gw.y >> 16);
;             const f32x4 v = acc[ei][tk] * rstd[tk] * w4;
;             float y0 = v[0] * siluf(g0), y1 = v[1] * siluf(g1), y2 = v[2] * siluf(g2), y3 = v[3] * siluf(g3);
;     ...
;             if (!(fabsf(y0) < 1e30f)) y0 = 0.f; if (!(fabsf(y1) < 1e30f)) y1 = 0.f; if (!(fabsf(y2) < 1e30f)) y2 = 0.f; if (!(fabsf(y3) < 1e30f)) y3 = 0.f;
;     ...
;             u32x2 o; o.x = pk2(y0, y1); o.y = pk2(y2, y3);
;             *(u32x2*)(Y + row * LDY + ycol + e0) = o; } }
	v_cvt_pk_bf16_f32 v18, v18, v19
	v_cvt_pk_bf16_f32 v19, v20, v21
	v_lshl_add_u64 v[26:27], v[80:81], 0, v[22:23]
	global_store_dwordx2 v[54:55], v[18:19], off offset:64 nt
	v_lshlrev_b32_e32 v16, 16, v154
	v_and_b32_e32 v24, 0xffff0000, v154
	v_lshlrev_b32_e32 v28, 16, v155
	v_and_b32_e32 v25, 0xffff0000, v155
	v_mul_f32_e32 v29, 0xbfb8aa3b, v16
	v_mul_f32_e32 v30, 0xbfb8aa3b, v24
	v_mul_f32_e32 v31, 0xbfb8aa3b, v28
	v_mul_f32_e32 v32, 0xbfb8aa3b, v25
	v_exp_f32_e32 v29, v29
	v_exp_f32_e32 v30, v30
	v_exp_f32_e32 v31, v31
	v_exp_f32_e32 v32, v32
	v_add_f32_e32 v29, 1.0, v29
	v_add_f32_e32 v30, 1.0, v30
	v_add_f32_e32 v31, 1.0, v31
	v_add_f32_e32 v32, 1.0, v32
	v_rcp_f32_e32 v29, v29
	v_rcp_f32_e32 v30, v30
	v_rcp_f32_e32 v31, v31
	v_rcp_f32_e32 v32, v32
	v_pk_mul_f32 v[12:13], v[12:13], v[172:173]
	v_mul_f32_e32 v16, v29, v16
	v_mul_f32_e32 v24, v30, v24
	v_pk_mul_f32 v[14:15], v[14:15], v[174:175]
	v_mul_f32_e32 v28, v31, v28
	v_mul_f32_e32 v25, v32, v25
	v_mul_f32_e32 v12, v12, v16
	v_mul_f32_e32 v13, v13, v24
	v_mul_f32_e32 v14, v14, v28
	v_mul_f32_e32 v15, v15, v25
	v_cvt_pk_bf16_f32 v12, v12, v13
	v_cvt_pk_bf16_f32 v13, v14, v15
	global_store_dwordx2 v[78:79], v[12:13], off offset:96 nt
	v_pk_mul_f32 v[8:9], v[8:9], v[172:173]
	v_pk_mul_f32 v[10:11], v[10:11], v[174:175]
	v_lshl_add_u64 v[14:15], v[68:69], 0, v[22:23]
	v_pk_mul_f32 v[4:5], v[4:5], v[172:173]
	v_pk_mul_f32 v[6:7], v[6:7], v[174:175]
	v_pk_mul_f32 v[0:1], v[0:1], v[172:173]
	v_pk_mul_f32 v[2:3], v[2:3], v[174:175]
	v_lshlrev_b32_e32 v16, 16, v158
	v_and_b32_e32 v12, 0xffff0000, v158
	v_lshlrev_b32_e32 v24, 16, v159
	v_and_b32_e32 v13, 0xffff0000, v159
	v_mul_f32_e32 v25, 0xbfb8aa3b, v16
	v_mul_f32_e32 v26, 0xbfb8aa3b, v12
	v_mul_f32_e32 v27, 0xbfb8aa3b, v24
	v_mul_f32_e32 v28, 0xbfb8aa3b, v13
	v_exp_f32_e32 v25, v25
	v_exp_f32_e32 v26, v26
	v_exp_f32_e32 v27, v27
	v_exp_f32_e32 v28, v28
	v_add_f32_e32 v25, 1.0, v25
	v_add_f32_e32 v26, 1.0, v26
	v_add_f32_e32 v27, 1.0, v27
	v_add_f32_e32 v28, 1.0, v28
	v_rcp_f32_e32 v25, v25
	v_rcp_f32_e32 v26, v26
	v_rcp_f32_e32 v27, v27
	v_rcp_f32_e32 v28, v28
	v_mul_f32_e32 v16, v25, v16
	v_mul_f32_e32 v12, v26, v12
	v_mul_f32_e32 v24, v27, v24
	v_mul_f32_e32 v13, v28, v13
	v_mul_f32_e32 v8, v8, v16
	v_mul_f32_e32 v9, v9, v12
	v_mul_f32_e32 v10, v10, v24
	v_mul_f32_e32 v11, v11, v13
	v_cvt_pk_bf16_f32 v8, v8, v9
	v_cvt_pk_bf16_f32 v9, v10, v11
	global_store_dwordx2 v[66:67], v[8:9], off offset:96 nt
	v_lshl_add_u64 v[10:11], v[60:61], 0, v[22:23]
	v_lshlrev_b32_e32 v12, 16, v166
	v_and_b32_e32 v8, 0xffff0000, v166
	v_lshlrev_b32_e32 v13, 16, v167
	v_and_b32_e32 v9, 0xffff0000, v167
	v_mul_f32_e32 v14, 0xbfb8aa3b, v12
	v_mul_f32_e32 v15, 0xbfb8aa3b, v8
	v_mul_f32_e32 v16, 0xbfb8aa3b, v13
	v_mul_f32_e32 v22, 0xbfb8aa3b, v9
	v_exp_f32_e32 v14, v14
	v_exp_f32_e32 v15, v15
	v_exp_f32_e32 v16, v16
	v_exp_f32_e32 v22, v22
	v_add_f32_e32 v14, 1.0, v14
	v_add_f32_e32 v15, 1.0, v15
	v_add_f32_e32 v16, 1.0, v16
	v_add_f32_e32 v22, 1.0, v22
	v_rcp_f32_e32 v14, v14
	v_rcp_f32_e32 v15, v15
	v_rcp_f32_e32 v16, v16
	v_rcp_f32_e32 v22, v22
	v_mul_f32_e32 v12, v14, v12
	v_mul_f32_e32 v8, v15, v8
	v_mul_f32_e32 v13, v16, v13
	v_mul_f32_e32 v9, v22, v9
	v_mul_f32_e32 v4, v4, v12
	v_mul_f32_e32 v5, v5, v8
	v_mul_f32_e32 v6, v6, v13
	v_mul_f32_e32 v7, v7, v9
	v_cvt_pk_bf16_f32 v4, v4, v5
	v_cvt_pk_bf16_f32 v5, v6, v7
	global_store_dwordx2 v[58:59], v[4:5], off offset:96 nt
	v_lshlrev_b32_e32 v6, 16, v178
	v_and_b32_e32 v4, 0xffff0000, v178
	v_lshlrev_b32_e32 v7, 16, v179
	v_and_b32_e32 v5, 0xffff0000, v179
	v_mul_f32_e32 v8, 0xbfb8aa3b, v6
	v_mul_f32_e32 v9, 0xbfb8aa3b, v4
	v_mul_f32_e32 v10, 0xbfb8aa3b, v7
	v_mul_f32_e32 v11, 0xbfb8aa3b, v5
	v_exp_f32_e32 v8, v8
	v_exp_f32_e32 v9, v9
	v_exp_f32_e32 v10, v10
	v_exp_f32_e32 v11, v11
	v_add_f32_e32 v8, 1.0, v8
	v_add_f32_e32 v9, 1.0, v9
	v_add_f32_e32 v10, 1.0, v10
	v_add_f32_e32 v11, 1.0, v11
	v_rcp_f32_e32 v8, v8
	v_rcp_f32_e32 v9, v9
	v_rcp_f32_e32 v10, v10
	v_rcp_f32_e32 v11, v11
	v_mul_f32_e32 v6, v8, v6
	v_mul_f32_e32 v4, v9, v4
	v_mul_f32_e32 v7, v10, v7
	v_mul_f32_e32 v5, v11, v5
	v_mul_f32_e32 v0, v0, v6
	v_mul_f32_e32 v1, v1, v4
	v_mul_f32_e32 v2, v2, v7
	v_mul_f32_e32 v3, v3, v5
	v_cvt_pk_bf16_f32 v0, v0, v1
	v_cvt_pk_bf16_f32 v1, v2, v3
	global_store_dwordx2 v[54:55], v[0:1], off offset:96 nt
	v_mov_b32_e32 v18, v172
	v_mov_b32_e32 v19, v173
	v_mov_b32_e32 v20, v174
	v_mov_b32_e32 v21, v175
	v_mov_b32_e32 v34, v128
	v_mov_b32_e32 v35, v129
	v_mov_b32_e32 v36, v130
	v_mov_b32_e32 v37, v131
	v_mov_b32_e32 v50, v232
	v_mov_b32_e32 v51, v233
	v_mov_b32_e32 v52, v234
	v_mov_b32_e32 v53, v235
	v_mov_b32_e32 v110, v214
	v_mov_b32_e32 v111, v215
	s_waitcnt vmcnt(0) lgkmcnt(0)
	s_barrier
	s_cbranch_scc0 .LBB0_853
; #define LAS __attribute__((address_space(3)))
; template <int TY> __device__ __forceinline__ void mc_item(const Params& p, ldsp lds, int item) {
;     ...
;     const int bh = item >> 5, c = item & 31, b = bh >> 2, h = bh & 3, sc = c / NB, jc = c % NB, row0 = b * 2048 + c * 64;
;     ...
;     if (TY != 2) lds += LDSSHIFT;
;     ...
;     ldsp QX = lds, QH2 = lds + o_qh, KTs = lds + o_kt, VTs = lds + o_vt, Pm = lds + o_pm; LAS float* RED = (LAS float*)(lds + o_red);
;     const bf16_t* Pb = (const bf16_t*)(p.ws + WS_P);
;     constexpr int PP = TY == 2 ? NO : NE;
;     const int ecol = TY ? 256 + h * 128 : h * 64;
;     if (TY == 2) stage_rows<DK>(QX, PQ, Pb + (size_t)row0 * NO + O_Q + h * 256, NO, tid);
;     else { stage_rows<DK>(QX, PQ, (const bf16_t*)(p.ws + WS_QT) + (size_t)row0 * 768 + ecol, 768, tid);
;            stage_rows<DK>(QH2, PQ, (const bf16_t*)(p.ws + WS_QH) + (size_t)row0 * 768 + ecol, 768, tid); }
;     f32x4 acc[ET][4];
; #pragma unroll
;     for (int ei = 0; ei < ET; ++ei)
; #pragma unroll
;         for (int tk = 0; tk < 4; ++tk) acc[ei][tk] = (f32x4){0.f, 0.f, 0.f, 0.f};
;     const int voff = TY == 0 ? E_VA + h * 128 : (TY == 1 ? E_IB + h * 128 : O_V + h * 512);
;     const int tt = wave & 3, sp = wave >> 2;
;     u32x4 kr[TY == 2 ? 4 : 1], vr[TY == 2 ? 8 : 1];
;     if constexpr (TY == 2) { const size_t rowq = (size_t)b * 2048 + (sc * NB) * 64;
;         ld_rows<256>(kr, Pb + rowq * NO + O_K + h * 256, NO, tid); ld_T<512>(vr, Pb + rowq * NO + voff, NO, wave, lane); }
.LBB0_878:
	s_lshr_b32 s0, s37, 8
	s_add_i32 s1, s37, s0
	s_and_b32 s40, s1, 31
	s_ashr_i32 s20, s37, 7
	v_mov_b32_e32 v152, v161
	s_lshl_b32 s10, s20, 11
	s_lshl_b32 s11, s40, 6
	s_ashr_i32 s8, s37, 5
	s_or_b32 s58, s11, s10
	v_ashrrev_i32_e32 v0, 31, v152
	s_and_b32 s9, s8, 3
	s_mul_i32 s11, s58, 0x3000
	v_lshrrev_b32_e32 v0, 27, v0
	s_mul_hi_i32 s10, s58, 0x3000
	s_add_u32 s11, s26, s11
	v_add_u32_e32 v0, v152, v0
	s_addc_u32 s12, s27, s10
	s_lshl_b32 s59, s9, 9
	v_ashrrev_i32_e32 v62, 5, v0
	v_and_b32_e32 v0, 0xffffffe0, v0
	s_add_u32 s10, s11, s59
	v_sub_u32_e32 v60, v152, v0
	s_addc_u32 s11, s12, 0
	v_lshlrev_b32_e32 v42, 3, v60
	v_mov_b64_e32 v[4:5], s[10:11]
	v_ashrrev_i32_e32 v43, 31, v42
	v_mad_i64_i32 v[0:1], s[10:11], v62, s56, v[4:5]
	v_lshlrev_b64 v[6:7], 1, v[42:43]
	v_lshl_add_u64 v[0:1], v[0:1], 0, v[6:7]
	global_load_dwordx4 v[134:137], v[0:1], off nt
	s_movk_i32 s16, 0x108
	v_mad_u64_u32 v[8:9], s[10:11], v62, s16, v[42:43]
	v_lshl_add_u32 v8, v8, 1, 0
	s_ashr_i32 s21, s20, 31
	s_and_b32 s14, s1, 28
	s_lshl_b32 s14, s14, 6
	v_readfirstlane_b32 s60, v152
	s_ashr_i32 s12, s60, 6
	s_and_b32 s13, s1, 3
	s_lshl_b32 s9, s9, 10
	v_bfe_u32 v70, v152, 5, 1
	v_lshl_add_u32 v206, v60, 4, 0
	v_and_b32_e32 v150, 15, v152
	v_bfe_u32 v68, v152, 4, 2
	v_lshlrev_b32_e32 v138, 3, v68
	v_lshlrev_b32_e32 v151, 2, v68
	v_and_b32_e32 v153, 48, v152
	v_mul_u32_u24_e32 v225, 0x90, v150
	s_nop 0
	v_mov_b32_e32 v148, v8
	v_add_u32_e32 v0, 0x200, v152
	v_ashrrev_i32_e32 v1, 31, v0
	v_lshrrev_b32_e32 v1, 27, v1
	v_add_u32_e32 v1, v0, v1
	v_ashrrev_i32_e32 v63, 5, v1
	v_and_b32_e32 v1, 0xffffffe0, v1
	v_sub_u32_e32 v61, v0, v1
	v_lshlrev_b32_e32 v44, 3, v61
	v_ashrrev_i32_e32 v45, 31, v44
	v_mad_i64_i32 v[0:1], s[10:11], v63, s56, v[4:5]
	v_lshlrev_b64 v[8:9], 1, v[44:45]
	v_lshl_add_u64 v[0:1], v[0:1], 0, v[8:9]
	global_load_dwordx4 v[140:143], v[0:1], off nt
	v_mad_u64_u32 v[10:11], s[10:11], v63, s16, v[44:45]
	v_lshl_add_u32 v10, v10, 1, 0
	v_lshl_add_u32 v207, v61, 4, 0
	s_nop 0
	v_mov_b32_e32 v149, v10
	v_add_u32_e32 v0, 0x400, v152
	v_ashrrev_i32_e32 v1, 31, v0
	v_lshrrev_b32_e32 v1, 27, v1
	v_add_u32_e32 v1, v0, v1
	v_ashrrev_i32_e32 v64, 5, v1
	v_and_b32_e32 v1, 0xffffffe0, v1
	v_sub_u32_e32 v66, v0, v1
	v_lshlrev_b32_e32 v50, 3, v66
	v_ashrrev_i32_e32 v51, 31, v50
	v_mad_i64_i32 v[0:1], s[10:11], v64, s56, v[4:5]
	v_lshlrev_b64 v[10:11], 1, v[50:51]
	v_lshl_add_u64 v[0:1], v[0:1], 0, v[10:11]
	global_load_dwordx4 v[144:147], v[0:1], off nt
	v_mad_u64_u32 v[12:13], s[10:11], v64, s16, v[50:51]
	v_lshl_add_u32 v12, v12, 1, 0
	v_lshl_add_u32 v208, v66, 4, 0
	s_nop 0
	v_mov_b32_e32 v162, v12
	v_add_u32_e32 v0, 0x600, v152
	v_ashrrev_i32_e32 v1, 31, v0
	v_lshrrev_b32_e32 v1, 27, v1
	v_add_u32_e32 v1, v0, v1
	v_ashrrev_i32_e32 v65, 5, v1
	v_and_b32_e32 v1, 0xffffffe0, v1
	v_sub_u32_e32 v67, v0, v1
	v_lshlrev_b32_e32 v52, 3, v67
	v_ashrrev_i32_e32 v53, 31, v52
	v_mad_i64_i32 v[0:1], s[10:11], v65, s56, v[4:5]
	v_lshlrev_b64 v[4:5], 1, v[52:53]
	v_lshl_add_u64 v[0:1], v[0:1], 0, v[4:5]
	global_load_dwordx4 v[154:157], v[0:1], off nt
	v_mad_u64_u32 v[12:13], s[10:11], v65, s16, v[52:53]
	s_lshl_b64 s[10:11], s[20:21], 11
	s_or_b32 s10, s10, s14
	s_mulk_i32 s11, 0x3000
	s_mul_hi_u32 s14, s10, 0x3000
	s_add_i32 s14, s14, s11
	s_mulk_i32 s10, 0x3000
	s_add_u32 s15, s26, s10
	s_addc_u32 s14, s27, s14
	s_add_u32 s10, s15, s59
	v_lshl_add_u32 v12, v12, 1, 0
	s_addc_u32 s11, s14, 0
	s_bitset1_b32 s9, 12
	v_lshl_add_u32 v210, v67, 4, 0
	s_nop 0
	v_mov_b32_e32 v163, v12
	v_mov_b64_e32 v[0:1], s[10:11]
	v_mad_i64_i32 v[2:3], s[10:11], v62, s56, v[0:1]
	v_lshl_add_u64 v[2:3], v[2:3], 0, v[6:7]
	global_load_dwordx4 v[30:33], v[2:3], off offset:2048
	v_mad_i64_i32 v[2:3], s[10:11], v63, s56, v[0:1]
	v_lshl_add_u64 v[2:3], v[2:3], 0, v[8:9]
	global_load_dwordx4 v[34:37], v[2:3], off offset:2048
	v_mad_i64_i32 v[2:3], s[10:11], v64, s56, v[0:1]
	v_mad_i64_i32 v[0:1], s[10:11], v65, s56, v[0:1]
	v_lshl_add_u64 v[2:3], v[2:3], 0, v[10:11]
	v_lshl_add_u64 v[0:1], v[0:1], 0, v[4:5]
	s_add_u32 s10, s15, s9
	global_load_dwordx4 v[38:41], v[2:3], off offset:2048
	global_load_dwordx4 v[46:49], v[0:1], off offset:2048
	s_addc_u32 s11, s14, 0
	s_lshl_b32 s9, s12, 5
	v_and_b32_e32 v0, 31, v152
	v_and_or_b32 v69, s9, 32, v0
	s_and_b32 s9, s12, 0x1ffffffe
	v_mul_u32_u24_e32 v0, 0x1800, v69
	v_or_b32_e32 v2, s9, v70
	v_lshlrev_b32_e32 v16, 1, v0
	v_lshlrev_b32_e32 v58, 3, v2
	v_lshl_add_u64 v[0:1], s[10:11], 0, v[16:17]
	v_ashrrev_i32_e32 v59, 31, v58
	v_lshl_add_u64 v[54:55], v[58:59], 1, v[0:1]
	global_load_dwordx4 v[26:29], v[54:55], off
	global_load_dwordx4 v[22:25], v[54:55], off offset:128
	global_load_dwordx4 v[18:21], v[54:55], off offset:256
	global_load_dwordx4 v[12:15], v[54:55], off offset:384
	global_load_dwordx4 v[8:11], v[54:55], off offset:512
	global_load_dwordx4 v[4:7], v[54:55], off offset:640
	global_load_dwordx4 v[0:3], v[54:55], off offset:768
	s_nop 0
	global_load_dwordx4 v[54:57], v[54:55], off offset:896
	s_waitcnt vmcnt(15)
	ds_write_b128 v148, v[134:137]
	s_waitcnt vmcnt(14)
	ds_write_b128 v149, v[140:143]
	s_waitcnt vmcnt(13)
	ds_write_b128 v162, v[144:147]
	s_waitcnt vmcnt(12)
	ds_write_b128 v163, v[154:157]
	s_movk_i32 s9, 0x210
	v_mul_lo_u32 v203, v62, s9
	v_mul_lo_u32 v204, v63, s9
	v_mul_lo_u32 v205, v64, s9
	v_mul_lo_u32 v209, v65, s9
	s_and_b32 s9, s12, 0x3fffffe
	v_or_b32_e32 v60, s9, v70
	s_movk_i32 s9, 0x240
	v_mul_lo_u32 v60, v60, s9
	s_lshl_b32 s9, s12, 4
	v_and_or_b32 v155, s9, 48, v150
	s_ashr_i32 s9, s60, 3
	v_or_b32_e32 v60, v69, v60
	v_readlane_b32 s14, v255, 22
	s_andn2_b32 s9, s9, 31
	v_or_b32_e32 v157, s9, v151
	v_lshl_add_u32 v162, v60, 1, s14
	v_or_b32_e32 v60, s9, v150
	v_mad_u64_u32 v[60:61], s[10:11], v60, s16, v[138:139]
	v_readlane_b32 s9, v255, 23
	v_mul_u32_u24_e32 v61, 0x48, v155
	v_mul_u32_u24_e32 v67, 0x108, v155
	v_add_u32_e32 v154, s9, v153
	s_and_b32 s9, s60, 0x7fffffc0
	v_add_u32_e32 v66, 0x1080, v60
	v_add_lshl_u32 v156, v157, v61, 1
	v_or_b32_e32 v61, s9, v150
	s_movk_i32 s9, 0x90
	v_add_u32_e32 v139, s14, v153
	s_cmp_lg_u32 s13, 0
	v_add_lshl_u32 v163, v67, v138, 1
	v_lshlrev_b32_e32 v218, 1, v60
	v_lshlrev_b32_e32 v219, 1, v66
	v_or_b32_e32 v220, 16, v157
	v_or_b32_e32 v221, 17, v157
	v_or_b32_e32 v222, 18, v157
	v_or_b32_e32 v223, 3, v157
	v_or_b32_e32 v224, 19, v157
	v_mul_lo_u32 v226, v61, s9
	s_cbranch_scc0 .LBB0_897
; template <int TY> __device__ __forceinline__ void mc_item(const Params& p, ldsp lds, int item) {
;     ...
;     f32x4 acc[ET][4];
; #pragma unroll
;     for (int ei = 0; ei < ET; ++ei)
; #pragma unroll
;         for (int tk = 0; tk < 4; ++tk) acc[ei][tk] = (f32x4){0.f, 0.f, 0.f, 0.f};
;     const int voff = TY == 0 ? E_VA + h * 128 : (TY == 1 ? E_IB + h * 128 : O_V + h * 512);
;     const int tt = wave & 3, sp = wave >> 2;
;     u32x4 kr[TY == 2 ? 4 : 1], vr[TY == 2 ? 8 : 1];
;     if constexpr (TY == 2) { const size_t rowq = (size_t)b * 2048 + (sc * NB) * 64;
;         ld_rows<256>(kr, Pb + rowq * NO + O_K + h * 256, NO, tid); ld_T<512>(vr, Pb + rowq * NO + voff, NO, wave, lane); }
;     for (int j = 0; j <= jc; ++j) { const size_t rowj = (size_t)b * 2048 + (sc * NB + j) * 64;
;         if constexpr (TY == 2) { st_rows<256>(KTs, PQ, kr, tid); st_T<512>(VTs, 72, vr, wave, lane); }
;         else { stage_rows<DK>(KTs, PQ, (const bf16_t*)(p.ws + WS_KT) + rowj * 768 + ecol, 768, tid);
;                stage_T<DV>(VTs, 72, Pb + rowj * PP + voff, PP, wave, lane); }
;         if constexpr (TY == 2) { __syncthreads(); if (j < jc) { const size_t rown = rowj + 64; ld_rows<256>(kr, Pb + rown * NO + O_K + h * 256, NO, tid); ld_T<512>(vr, Pb + rown * NO + voff, NO, wave, lane); } }
	s_movk_i32 s38, 0x90
	s_bfe_u32 s1, s1, 0x30002
	s_add_i32 s0, s36, s0
	s_mul_i32 s21, s1, 0x300000
	s_and_b32 s0, s0, 3
	v_mul_lo_u32 v202, v61, s38
	s_mul_hi_i32 s38, s20, 0x1800000
	s_mul_i32 s20, s20, 0x1800000
	s_add_u32 s39, s20, s21
	s_addc_u32 s21, s38, 0
	s_lshl_b32 s20, s37, 4
	s_and_b32 s20, s20, 0x600
	v_mad_i64_i32 v[68:69], s[10:11], v62, s56, 0
	s_or_b32 s20, s39, s20
	v_lshlrev_b32_e32 v217, 1, v60
	v_lshl_add_u64 v[60:61], s[20:21], 0, v[68:69]
	v_readlane_b32 s76, v254, 55
	v_mad_i64_i32 v[62:63], s[10:11], v63, s56, 0
	v_lshl_add_u64 v[42:43], v[42:43], 1, v[60:61]
	v_readlane_b32 s77, v254, 56
	v_mad_i64_i32 v[70:71], s[10:11], v64, s56, 0
	s_nop 0
	v_lshl_add_u64 v[140:141], s[76:77], 0, v[42:43]
	v_lshl_add_u64 v[42:43], s[20:21], 0, v[62:63]
	v_lshl_add_u64 v[42:43], v[44:45], 1, v[42:43]
	v_lshl_add_u64 v[142:143], s[76:77], 0, v[42:43]
	v_lshl_add_u64 v[42:43], s[20:21], 0, v[70:71]
	v_mad_i64_i32 v[64:65], s[10:11], v65, s56, 0
	v_lshl_add_u64 v[42:43], v[50:51], 1, v[42:43]
	v_lshl_add_u64 v[144:145], s[76:77], 0, v[42:43]
	v_lshl_add_u64 v[42:43], s[20:21], 0, v[64:65]
	s_lshl_b32 s20, s37, 5
	s_and_b32 s20, s20, 0xc00
	v_lshl_add_u64 v[42:43], v[52:53], 1, v[42:43]
	s_or_b32 s20, s39, s20
	v_lshl_add_u64 v[146:147], s[76:77], 0, v[42:43]
	v_mov_b32_e32 v42, s20
	v_mov_b32_e32 v43, s21
	v_lshl_add_u64 v[42:43], v[58:59], 1, v[42:43]
	v_readlane_b32 s20, v254, 57
	s_movk_i32 s10, 0xfff
	v_lshl_add_u64 v[42:43], v[42:43], 0, v[16:17]
	v_readlane_b32 s21, v254, 58
	s_mul_i32 s9, s0, 0xc0000
	v_cmp_lt_i32_e64 s[0:1], s57, v157
	v_or_b32_e32 v215, 16, v157
	v_cmp_lt_i32_e64 s[10:11], s10, v157
	v_or_b32_e32 v214, 17, v157
	v_or_b32_e32 v211, 18, v157
	v_or_b32_e32 v212, 3, v157
	v_or_b32_e32 v213, 19, v157
	v_lshl_add_u64 v[148:149], s[20:21], 0, v[42:43]
	v_mov_b32_e32 v42, 0
	s_waitcnt vmcnt(0)
	v_mov_b64_e32 v[100:101], v[56:57]
	v_mov_b64_e32 v[132:133], v[32:33]
	v_mov_b64_e32 v[128:129], v[36:37]
	v_mov_b64_e32 v[124:125], v[40:41]
	v_mov_b64_e32 v[120:121], v[48:49]
	v_lshlrev_b32_e32 v216, 1, v66
	v_cmp_lt_i32_e32 vcc, s57, v215
	v_cmp_lt_i32_e64 s[12:13], s57, v214
	v_cmp_lt_i32_e64 s[14:15], s57, v211
	v_cmp_lt_i32_e64 s[16:17], s57, v212
	v_cmp_lt_i32_e64 s[18:19], s57, v213
	v_mul_u32_u24_e32 v201, 0x90, v150
	v_add_u32_e32 v160, 0x900, v202
	v_add_u32_e32 v159, 0x1200, v202
	v_add_u32_e32 v158, 0x1b00, v202
	s_mov_b64 s[38:39], 0
	s_and_b64 s[20:21], s[10:11], s[0:1]
	v_mov_b64_e32 v[98:99], v[54:55]
	v_mov_b64_e32 v[130:131], v[30:31]
	v_mov_b64_e32 v[126:127], v[34:35]
	v_mov_b64_e32 v[122:123], v[38:39]
	v_mov_b64_e32 v[118:119], v[46:47]
	v_mov_b32_e32 v43, v42
	v_mov_b32_e32 v44, v42
	v_mov_b32_e32 v45, v42
	v_mov_b32_e32 v50, v42
	v_mov_b32_e32 v51, v42
	v_mov_b32_e32 v52, v42
	v_mov_b32_e32 v53, v42
	v_mov_b32_e32 v58, v42
	v_mov_b32_e32 v59, v42
	v_mov_b32_e32 v60, v42
	v_mov_b32_e32 v61, v42
	v_mov_b32_e32 v62, v42
	v_mov_b32_e32 v63, v42
	v_mov_b32_e32 v64, v42
	v_mov_b32_e32 v65, v42
	v_mov_b32_e32 v66, v42
	v_mov_b32_e32 v67, v42
	v_mov_b32_e32 v68, v42
	v_mov_b32_e32 v69, v42
	v_mov_b32_e32 v70, v42
	v_mov_b32_e32 v71, v42
	v_mov_b32_e32 v72, v42
	v_mov_b32_e32 v73, v42
	v_mov_b32_e32 v74, v42
	v_mov_b32_e32 v75, v42
	v_mov_b32_e32 v76, v42
	v_mov_b32_e32 v77, v42
	v_mov_b32_e32 v78, v42
	v_mov_b32_e32 v79, v42
	v_mov_b32_e32 v80, v42
	v_mov_b32_e32 v81, v42
	v_mov_b32_e32 v82, v42
	v_mov_b32_e32 v83, v42
	v_mov_b32_e32 v84, v42
	v_mov_b32_e32 v85, v42
	v_mov_b32_e32 v86, v42
	v_mov_b32_e32 v87, v42
	v_mov_b32_e32 v88, v42
	v_mov_b32_e32 v89, v42
	v_mov_b32_e32 v90, v42
	v_mov_b32_e32 v91, v42
	v_mov_b32_e32 v92, v42
	v_mov_b32_e32 v93, v42
	v_mov_b32_e32 v94, v42
	v_mov_b32_e32 v95, v42
	v_mov_b32_e32 v96, v42
	v_mov_b32_e32 v97, v42
	v_mov_b32_e32 v102, v42
	v_mov_b32_e32 v103, v42
	v_mov_b32_e32 v104, v42
	v_mov_b32_e32 v105, v42
	v_mov_b32_e32 v106, v42
	v_mov_b32_e32 v107, v42
	v_mov_b32_e32 v108, v42
	v_mov_b32_e32 v109, v42
	v_mov_b32_e32 v110, v42
	v_mov_b32_e32 v111, v42
	v_mov_b32_e32 v112, v42
	v_mov_b32_e32 v113, v42
	v_mov_b32_e32 v114, v42
	v_mov_b32_e32 v115, v42
	v_mov_b32_e32 v116, v42
	v_mov_b32_e32 v117, v42
